# attention tile loops: next tile's LDS fragment addresses formed before the tile barrier (loop-edge edit)
# baseline (speedup 1.0000x reference)
; DI f32x16 mfma32(bf16x8 a, bf16x8 b, f32x16 c) { return __builtin_amdgcn_mfma_f32_32x32x16_bf16(a, b, c, 0, 0, 0); }
; template <int DQK, int DV, bool NA>
; DI void attend(const bf16_t* __restrict__ Q, int q0, const bf16_t* __restrict__ Kb, const bf16_t* __restrict__ Vb,
;                int s0, int n0, int s1, int n1, f32x16 (&o)[DV / 32], char* smem, NAInfo na) {
;     ...
;         const char* sK = smem + (t & 1) * ATT_LDS; const char* sV = sK + 64 * KS;
;         bool active = true; int kr = 0;
;         if (NA && t < n0) { kr = na.kstart + t; active = (kr >= rs) && (kr < rs + 8); }
;         if (active) {
; #pragma unroll
;             for (int sub = 0; sub < 2; ++sub) {
;                 f32x16 st;
;                 if (NA) {
; #pragma unroll
;                     for (int r = 0; r < 16; ++r) st[r] = 0.f;
;                 } else st = cinit;
;                 {
;                     bf16x8 kf[NS];
; #pragma unroll
;                     for (int s = 0; s < NS; ++s) kf[s] = *(const bf16x8*)(sK + (sub * 32 + l31) * KS + (s * 16 + hh * 8) * 2);
;                     __builtin_amdgcn_sched_barrier(0);
; #pragma unroll
;                     for (int s = 0; s < NS; ++s) st = mfma32(kf[s], qf[s], st);
;                 }
;                 bf16x8 vf[NDT][2];
; #pragma unroll
;                 for (int d = 0; d < NDT; ++d)
; #pragma unroll
;                     for (int s2 = 0; s2 < 2; ++s2) {
;                         const char* vp = sV + (sub * 32 + 16 * s2 + 4 * hh + q) * VS + (d * 32 + dblk * 16 + 4 * p) * 2;
;                         vf[d][s2] = cat8(tr_read(vp), tr_read(vp + 8 * VS));
;                     }
;                 if (NA && t < n0) {
;                     const float* brow = rpb + (kr - na.qr + 7) * 31 + 15 - qc;
; #pragma unroll
;                     for (int r = 0; r < 16; ++r) {
;                         const int kc = sub * 32 + (r & 3) + 8 * (r >> 2) + 4 * hh;
;                         const bool valid = (kc >= cs) && (kc < cs + 16);
;                         const int bi = valid ? kc : cs;
;                         const float bias = brow[bi];
;                         st[r] = valid ? st[r] + bias : -INFINITY;
;                     }
;                 }
;                 float mx = st[0];
; #pragma unroll
;                 for (int r = 1; r < 16; ++r) mx = fmaxf(mx, st[r]);
;                 mx = xor32_max(mx);
.LBB0_109:
	s_add_i32 s4, s2, 1
	s_and_b32 s4, s4, 1
	s_mul_i32 s4, s4, 0x8400
	v_add_u32_e32 v154, s4, v172
	v_add_u32_e32 v155, s4, v152
	v_add_u32_e32 v154, v154, v151
	v_add_u32_e32 v155, v155, v150
.Lmy_mla_top:
	s_add_i32 s2, s2, 1
	s_and_b32 s3, s2, 1
	ds_read_b128 v[116:119], v154
	ds_read_b128 v[120:123], v154 offset:32
	ds_read_b128 v[124:127], v154 offset:64
	ds_read_b128 v[128:131], v154 offset:96
	ds_read_b128 v[156:159], v154 offset:128
	ds_read_b128 v[160:163], v154 offset:160
	s_waitcnt lgkmcnt(5)
	v_mfma_f32_32x32x16_bf16 v[64:79], v[116:119], v[100:103], v[48:63]
	ds_read_b128 v[116:119], v154 offset:6656
	s_waitcnt lgkmcnt(5)
	v_mfma_f32_32x32x16_bf16 v[64:79], v[120:123], v[96:99], v[64:79]
	ds_read_b128 v[120:123], v154 offset:6688
	s_waitcnt lgkmcnt(5)
	v_mfma_f32_32x32x16_bf16 v[64:79], v[124:127], v[92:95], v[64:79]
	ds_read_b128 v[124:127], v154 offset:6720
	s_waitcnt lgkmcnt(5)
	v_mfma_f32_32x32x16_bf16 v[64:79], v[128:131], v[88:91], v[64:79]
	ds_read_b128 v[128:131], v154 offset:6752
	s_waitcnt lgkmcnt(5)
	v_mfma_f32_32x32x16_bf16 v[64:79], v[156:159], v[84:87], v[64:79]
	ds_read_b128 v[156:159], v154 offset:6784
	s_waitcnt lgkmcnt(5)
	v_mfma_f32_32x32x16_bf16 v[64:79], v[160:163], v[80:83], v[64:79]
	ds_read_b128 v[160:163], v154 offset:6816
	ds_read_b64_tr_b16 v[242:243], v155 offset:13312
	ds_read_b64_tr_b16 v[244:245], v155 offset:14848
	ds_read_b64_tr_b16 v[246:247], v155 offset:13376
	ds_read_b64_tr_b16 v[248:249], v155 offset:14912
	s_nop 6
	v_max3_f32 v237, v64, v65, v66
	v_max3_f32 v238, v72, v73, v74
	v_max3_f32 v237, v237, v67, v68
	v_max3_f32 v238, v238, v75, v76
	v_max3_f32 v237, v237, v69, v70
	v_max3_f32 v238, v238, v77, v78
	v_max3_f32 v237, v237, v71, v79
	v_max_f32_e32 v237, v237, v238
	v_cmp_lt_f32_e32 vcc, 0x41000000, v237
	s_cbranch_vccnz .Lmy_mla_rare0

; DI unsigned pk2(float a, float b) { f32x2 v = {a, b}; bfx2 r = __builtin_convertvector(v, bfx2); return __builtin_bit_cast(unsigned, r); }
; DI f32x16 mfma32(bf16x8 a, bf16x8 b, f32x16 c) { return __builtin_amdgcn_mfma_f32_32x32x16_bf16(a, b, c, 0, 0, 0); }
; template <int DQK, int DV, bool NA>
; DI void attend(const bf16_t* __restrict__ Q, int q0, const bf16_t* __restrict__ Kb, const bf16_t* __restrict__ Vb,
;                int s0, int n0, int s1, int n1, f32x16 (&o)[DV / 32], char* smem, NAInfo na) {
;     ...
; #pragma unroll
;                     for (int r = 0; r < 16; ++r) { st[r] = __builtin_amdgcn_exp2f(st[r]); rsum += st[r]; }
;                 }
;                 l += rsum;
;                 bf16x8 pf[2];
; #pragma unroll
;                 for (int s2 = 0; s2 < 2; ++s2) {
;                     u32x4 w;
;                     w.x = pk2(st[8 * s2], st[8 * s2 + 1]); w.y = pk2(st[8 * s2 + 2], st[8 * s2 + 3]);
;                     w.z = pk2(st[8 * s2 + 4], st[8 * s2 + 5]); w.w = pk2(st[8 * s2 + 6], st[8 * s2 + 7]);
;                     pf[s2] = __builtin_bit_cast(bf16x8, w);
;                 }
; #pragma unroll
;                 for (int d = 0; d < NDT; ++d)
; #pragma unroll
;                     for (int s2 = 0; s2 < 2; ++s2) o[d] = mfma32(vf[d][s2], pf[s2], o[d]);
;             }
;         }
;         if (t + 1 < nt) lwrite(smem + ((t & 1) ^ 1) * ATT_LDS);
;         if (t + 2 < nt) gload(t + 2);
;         __syncthreads();
;     }
.Lmy_mla_res1:
	v_exp_f32_e32 v32, v32
	v_exp_f32_e32 v33, v33
	v_exp_f32_e32 v34, v34
	v_exp_f32_e32 v35, v35
	v_exp_f32_e32 v36, v36
	v_exp_f32_e32 v37, v37
	v_exp_f32_e32 v38, v38
	v_exp_f32_e32 v39, v39
	v_add_f32_e32 v158, v32, v33
	v_add_f32_e32 v158, v158, v34
	v_add_f32_e32 v158, v158, v35
	v_add_f32_e32 v158, v158, v36
	v_add_f32_e32 v158, v158, v37
	v_add_f32_e32 v158, v158, v38
	v_add_f32_e32 v158, v158, v39
	v_cvt_pk_bf16_f32 v32, v32, v33
	v_cvt_pk_bf16_f32 v33, v34, v35
	v_cvt_pk_bf16_f32 v34, v36, v37
	v_cvt_pk_bf16_f32 v35, v38, v39
	v_exp_f32_e32 v40, v40
	v_exp_f32_e32 v41, v41
	s_waitcnt lgkmcnt(4)
	v_mfma_f32_32x32x16_bf16 v[16:31], v[242:245], v[32:35], v[16:31]
	v_exp_f32_e32 v42, v42
	v_exp_f32_e32 v43, v43
	v_exp_f32_e32 v44, v44
	v_exp_f32_e32 v45, v45
	v_exp_f32_e32 v46, v46
	v_exp_f32_e32 v47, v47
	v_add_f32_e32 v159, v40, v41
	v_add_f32_e32 v159, v159, v42
	v_add_f32_e32 v159, v159, v43
	v_mfma_f32_32x32x16_bf16 v[0:15], v[246:249], v[32:35], v[0:15]
	v_add_f32_e32 v159, v159, v44
	v_add_f32_e32 v159, v159, v45
	v_add_f32_e32 v159, v159, v46
	v_add_f32_e32 v159, v159, v47
	v_cvt_pk_bf16_f32 v40, v40, v41
	v_cvt_pk_bf16_f32 v41, v42, v43
	v_cvt_pk_bf16_f32 v42, v44, v45
	v_cvt_pk_bf16_f32 v43, v46, v47
	v_add_f32_e32 v250, v250, v251
	v_add_f32_e32 v158, v158, v159
	s_waitcnt lgkmcnt(0)
	v_mfma_f32_32x32x16_bf16 v[16:31], v[116:119], v[40:43], v[16:31]
	s_xor_b32 s3, s3, 1
	s_mul_i32 s3, s3, 0x8400
	v_add_f32_e32 v250, v250, v158
	v_add3_u32 v160, s3, v142, v143
	v_add3_u32 v161, s3, v144, v145
	v_add3_u32 v162, s3, v146, v147
	v_add_f32_e32 v132, v132, v250
	v_add_u32_e32 v154, s3, v172
	v_add_u32_e32 v155, s3, v152
	v_add_u32_e32 v154, v154, v151
	v_add_u32_e32 v155, v155, v150
	s_waitcnt vmcnt(2)
	ds_write_b128 v160, v[104:107]
	v_mfma_f32_32x32x16_bf16 v[0:15], v[120:123], v[40:43], v[0:15]
	s_waitcnt vmcnt(1)
	ds_write_b128 v161, v[108:111]
	s_waitcnt vmcnt(0)
	ds_write_b128 v162, v[112:115] offset:13312
	global_load_dwordx4 v[104:107], v[138:139], off
	global_load_dwordx4 v[108:111], v[136:137], off
	global_load_dwordx4 v[112:115], v[134:135], off
	s_mov_b64 s[4:5], 0x3000
	v_lshl_add_u64 v[138:139], v[138:139], 0, s[4:5]
	v_lshl_add_u64 v[136:137], v[136:137], 0, s[4:5]
	v_lshl_add_u64 v[134:135], v[134:135], 0, s[82:83]
	v_cmp_eq_u32_e32 vcc, s2, v153
	v_mov_b32_e32 v64, s2
	s_or_b64 s[0:1], vcc, s[0:1]
	s_waitcnt lgkmcnt(0)
	s_barrier
	s_cbranch_vccz .Lmy_mla_top
	v_mov_b64_e32 v[32:33], v[48:49]
	v_mov_b64_e32 v[34:35], v[50:51]
	v_mov_b64_e32 v[36:37], v[52:53]
	v_mov_b64_e32 v[38:39], v[54:55]
	v_mov_b64_e32 v[40:41], v[56:57]
	v_mov_b64_e32 v[42:43], v[58:59]
	v_mov_b64_e32 v[44:45], v[60:61]
	v_mov_b64_e32 v[46:47], v[62:63]
	s_branch .LBB0_114

; DI f32x16 mfma32(bf16x8 a, bf16x8 b, f32x16 c) { return __builtin_amdgcn_mfma_f32_32x32x16_bf16(a, b, c, 0, 0, 0); }
; template <int DQK, int DV, bool NA>
; DI void attend(const bf16_t* __restrict__ Q, int q0, const bf16_t* __restrict__ Kb, const bf16_t* __restrict__ Vb,
;                int s0, int n0, int s1, int n1, f32x16 (&o)[DV / 32], char* smem, NAInfo na) {
;     ...
;         const char* sK = smem + (t & 1) * ATT_LDS; const char* sV = sK + 64 * KS;
;         bool active = true; int kr = 0;
;         if (NA && t < n0) { kr = na.kstart + t; active = (kr >= rs) && (kr < rs + 8); }
;         if (active) {
; #pragma unroll
;             for (int sub = 0; sub < 2; ++sub) {
;                 f32x16 st;
;                 if (NA) {
; #pragma unroll
;                     for (int r = 0; r < 16; ++r) st[r] = 0.f;
;                 } else st = cinit;
;                 {
;                     bf16x8 kf[NS];
; #pragma unroll
;                     for (int s = 0; s < NS; ++s) kf[s] = *(const bf16x8*)(sK + (sub * 32 + l31) * KS + (s * 16 + hh * 8) * 2);
;                     __builtin_amdgcn_sched_barrier(0);
; #pragma unroll
;                     for (int s = 0; s < NS; ++s) st = mfma32(kf[s], qf[s], st);
;                 }
;                 bf16x8 vf[NDT][2];
; #pragma unroll
;                 for (int d = 0; d < NDT; ++d)
; #pragma unroll
;                     for (int s2 = 0; s2 < 2; ++s2) {
;                         const char* vp = sV + (sub * 32 + 16 * s2 + 4 * hh + q) * VS + (d * 32 + dblk * 16 + 4 * p) * 2;
;                         vf[d][s2] = cat8(tr_read(vp), tr_read(vp + 8 * VS));
;                     }
;                 if (NA && t < n0) {
;                     const float* brow = rpb + (kr - na.qr + 7) * 31 + 15 - qc;
; #pragma unroll
;                     for (int r = 0; r < 16; ++r) {
;                         const int kc = sub * 32 + (r & 3) + 8 * (r >> 2) + 4 * hh;
;                         const bool valid = (kc >= cs) && (kc < cs + 16);
;                         const int bi = valid ? kc : cs;
;                         const float bias = brow[bi];
;                         st[r] = valid ? st[r] + bias : -INFINITY;
;                     }
;                 }
;                 float mx = st[0];
; #pragma unroll
;                 for (int r = 1; r < 16; ++r) mx = fmaxf(mx, st[r]);
;                 mx = xor32_max(mx);
.LBB0_132:
	s_add_i32 s2, s0, 1
	s_and_b32 s2, s2, 1
	s_mul_i32 s2, s2, 0x8400
	v_add_u32_e32 v238, s2, v172
	v_add_u32_e32 v237, s2, v236
	v_add_u32_e32 v238, v238, v234
	v_add_u32_e32 v237, v237, v235
.Lmy_d1_top:
	s_add_i32 s0, s0, 1
	s_and_b32 s1, s0, 1
	ds_read_b128 v[140:143], v238
	ds_read_b128 v[144:147], v238 offset:32
	ds_read_b128 v[148:151], v238 offset:64
	ds_read_b128 v[152:155], v238 offset:96
	s_waitcnt lgkmcnt(3)
	v_mfma_f32_32x32x16_bf16 v[96:111], v[140:143], v[120:123], v[80:95]
	ds_read_b128 v[140:143], v238 offset:4608
	s_waitcnt lgkmcnt(3)
	v_mfma_f32_32x32x16_bf16 v[96:111], v[144:147], v[124:127], v[96:111]
	ds_read_b128 v[144:147], v238 offset:4640
	s_waitcnt lgkmcnt(3)
	v_mfma_f32_32x32x16_bf16 v[96:111], v[148:151], v[116:119], v[96:111]
	ds_read_b128 v[148:151], v238 offset:4672
	s_waitcnt lgkmcnt(3)
	v_mfma_f32_32x32x16_bf16 v[96:111], v[152:155], v[112:115], v[96:111]
	ds_read_b128 v[152:155], v238 offset:4704
	ds_read_b64_tr_b16 v[156:157], v237 offset:9216
	ds_read_b64_tr_b16 v[158:159], v237 offset:11776
	ds_read_b64_tr_b16 v[160:161], v237 offset:9280
	ds_read_b64_tr_b16 v[162:163], v237 offset:11840
	ds_read_b64_tr_b16 v[164:165], v237 offset:9344
	ds_read_b64_tr_b16 v[166:167], v237 offset:11904
	ds_read_b64_tr_b16 v[168:169], v237 offset:9408
	ds_read_b64_tr_b16 v[170:171], v237 offset:11968
	s_nop 2
	v_max3_f32 v239, v96, v97, v98
	v_max3_f32 v240, v104, v105, v106
	v_max3_f32 v239, v239, v99, v100
	v_max3_f32 v240, v240, v107, v108
	v_max3_f32 v239, v239, v101, v102
	v_max3_f32 v240, v240, v109, v110
	v_max3_f32 v239, v239, v103, v111
	v_max_f32_e32 v239, v239, v240
	v_cmp_lt_f32_e32 vcc, 0x41000000, v239
	s_cbranch_vccnz .Lmy_d1_rare0

; DI unsigned pk2(float a, float b) { f32x2 v = {a, b}; bfx2 r = __builtin_convertvector(v, bfx2); return __builtin_bit_cast(unsigned, r); }
; DI f32x16 mfma32(bf16x8 a, bf16x8 b, f32x16 c) { return __builtin_amdgcn_mfma_f32_32x32x16_bf16(a, b, c, 0, 0, 0); }
; template <int DQK, int DV, bool NA>
; DI void attend(const bf16_t* __restrict__ Q, int q0, const bf16_t* __restrict__ Kb, const bf16_t* __restrict__ Vb,
;                int s0, int n0, int s1, int n1, f32x16 (&o)[DV / 32], char* smem, NAInfo na) {
;     ...
; #pragma unroll
;                     for (int r = 0; r < 16; ++r) { st[r] = __builtin_amdgcn_exp2f(st[r]); rsum += st[r]; }
;                 }
;                 l += rsum;
;                 bf16x8 pf[2];
; #pragma unroll
;                 for (int s2 = 0; s2 < 2; ++s2) {
;                     u32x4 w;
;                     w.x = pk2(st[8 * s2], st[8 * s2 + 1]); w.y = pk2(st[8 * s2 + 2], st[8 * s2 + 3]);
;                     w.z = pk2(st[8 * s2 + 4], st[8 * s2 + 5]); w.w = pk2(st[8 * s2 + 6], st[8 * s2 + 7]);
;                     pf[s2] = __builtin_bit_cast(bf16x8, w);
;                 }
; #pragma unroll
;                 for (int d = 0; d < NDT; ++d)
; #pragma unroll
;                     for (int s2 = 0; s2 < 2; ++s2) o[d] = mfma32(vf[d][s2], pf[s2], o[d]);
;             }
;         }
;         if (t + 1 < nt) lwrite(smem + ((t & 1) ^ 1) * ATT_LDS);
;         if (t + 2 < nt) gload(t + 2);
;         __syncthreads();
;     }
.Lmy_d1_res1:
	v_exp_f32_e32 v64, v64
	v_exp_f32_e32 v65, v65
	v_exp_f32_e32 v66, v66
	v_exp_f32_e32 v67, v67
	v_exp_f32_e32 v68, v68
	v_exp_f32_e32 v69, v69
	v_exp_f32_e32 v70, v70
	v_exp_f32_e32 v71, v71
	v_add_f32_e32 v246, v64, v65
	v_add_f32_e32 v246, v246, v66
	v_add_f32_e32 v246, v246, v67
	v_add_f32_e32 v246, v246, v68
	v_add_f32_e32 v246, v246, v69
	v_add_f32_e32 v246, v246, v70
	v_add_f32_e32 v246, v246, v71
	v_cvt_pk_bf16_f32 v64, v64, v65
	v_cvt_pk_bf16_f32 v65, v66, v67
	v_cvt_pk_bf16_f32 v66, v68, v69
	v_cvt_pk_bf16_f32 v67, v70, v71
	v_exp_f32_e32 v72, v72
	v_exp_f32_e32 v73, v73
	s_waitcnt lgkmcnt(8)
	v_mfma_f32_32x32x16_bf16 v[48:63], v[156:159], v[64:67], v[48:63]
	v_exp_f32_e32 v74, v74
	v_exp_f32_e32 v75, v75
	v_exp_f32_e32 v76, v76
	v_exp_f32_e32 v77, v77
	v_exp_f32_e32 v78, v78
	v_mfma_f32_32x32x16_bf16 v[32:47], v[160:163], v[64:67], v[32:47]
	v_exp_f32_e32 v79, v79
	v_add_f32_e32 v247, v72, v73
	v_add_f32_e32 v247, v247, v74
	v_add_f32_e32 v247, v247, v75
	v_mfma_f32_32x32x16_bf16 v[16:31], v[164:167], v[64:67], v[16:31]
	v_add_f32_e32 v247, v247, v76
	v_add_f32_e32 v247, v247, v77
	v_add_f32_e32 v247, v247, v78
	v_add_f32_e32 v247, v247, v79
	v_mfma_f32_32x32x16_bf16 v[0:15], v[168:171], v[64:67], v[0:15]
	v_cvt_pk_bf16_f32 v72, v72, v73
	v_cvt_pk_bf16_f32 v73, v74, v75
	v_cvt_pk_bf16_f32 v74, v76, v77
	v_cvt_pk_bf16_f32 v75, v78, v79
	v_add_f32_e32 v244, v244, v245
	v_add_f32_e32 v246, v246, v247
	s_waitcnt lgkmcnt(0)
	v_mfma_f32_32x32x16_bf16 v[48:63], v[140:143], v[72:75], v[48:63]
	s_xor_b32 s1, s1, 1
	s_mul_i32 s1, s1, 0x8400
	v_add_f32_e32 v244, v244, v246
	v_add3_u32 v248, s1, v227, v228
	v_add3_u32 v249, s1, v229, v230
	v_add3_u32 v250, s1, v231, v232
	v_add_f32_e32 v182, v182, v244
	v_mfma_f32_32x32x16_bf16 v[32:47], v[144:147], v[72:75], v[32:47]
	v_add_u32_e32 v238, s1, v172
	v_add_u32_e32 v237, s1, v236
	v_add_u32_e32 v238, v238, v234
	v_add_u32_e32 v237, v237, v235
	s_waitcnt vmcnt(2)
	ds_write_b128 v248, v[128:131]
	v_mfma_f32_32x32x16_bf16 v[16:31], v[148:151], v[72:75], v[16:31]
	s_waitcnt vmcnt(1)
	ds_write_b128 v249, v[132:135] offset:9216
	s_waitcnt vmcnt(0)
	ds_write_b128 v250, v[136:139] offset:9216
	global_load_dwordx4 v[128:131], v[192:193], off
	global_load_dwordx4 v[132:135], v[190:191], off
	v_mfma_f32_32x32x16_bf16 v[0:15], v[152:155], v[72:75], v[0:15]
	global_load_dwordx4 v[136:139], v[188:189], off
	s_mov_b64 s[2:3], 0x4000
	v_lshl_add_u64 v[192:193], v[192:193], 0, s[82:83]
	v_lshl_add_u64 v[190:191], v[190:191], 0, s[2:3]
	v_lshl_add_u64 v[188:189], v[188:189], 0, s[2:3]
	v_cmp_eq_u32_e32 vcc, s0, v217
	v_mov_b32_e32 v96, s0
	s_or_b64 s[4:5], vcc, s[4:5]
	s_waitcnt lgkmcnt(0)
	s_barrier
	s_cbranch_vccz .Lmy_d1_top
	v_mov_b64_e32 v[64:65], v[80:81]
	v_mov_b64_e32 v[66:67], v[82:83]
	v_mov_b64_e32 v[68:69], v[84:85]
	v_mov_b64_e32 v[70:71], v[86:87]
	v_mov_b64_e32 v[72:73], v[88:89]
	v_mov_b64_e32 v[74:75], v[90:91]
	v_mov_b64_e32 v[76:77], v[92:93]
	v_mov_b64_e32 v[78:79], v[94:95]
	s_branch .LBB0_137

; DI f32x16 mfma32(bf16x8 a, bf16x8 b, f32x16 c) { return __builtin_amdgcn_mfma_f32_32x32x16_bf16(a, b, c, 0, 0, 0); }
; template <int DQK, int DV, bool NA>
; DI void attend(const bf16_t* __restrict__ Q, int q0, const bf16_t* __restrict__ Kb, const bf16_t* __restrict__ Vb,
;                int s0, int n0, int s1, int n1, f32x16 (&o)[DV / 32], char* smem, NAInfo na) {
;     ...
;         const char* sK = smem + (t & 1) * ATT_LDS; const char* sV = sK + 64 * KS;
;         bool active = true; int kr = 0;
;         if (NA && t < n0) { kr = na.kstart + t; active = (kr >= rs) && (kr < rs + 8); }
;         if (active) {
; #pragma unroll
;             for (int sub = 0; sub < 2; ++sub) {
;                 f32x16 st;
;                 if (NA) {
; #pragma unroll
;                     for (int r = 0; r < 16; ++r) st[r] = 0.f;
;                 } else st = cinit;
;                 {
;                     bf16x8 kf[NS];
; #pragma unroll
;                     for (int s = 0; s < NS; ++s) kf[s] = *(const bf16x8*)(sK + (sub * 32 + l31) * KS + (s * 16 + hh * 8) * 2);
;                     __builtin_amdgcn_sched_barrier(0);
; #pragma unroll
;                     for (int s = 0; s < NS; ++s) st = mfma32(kf[s], qf[s], st);
;                 }
;                 bf16x8 vf[NDT][2];
; #pragma unroll
;                 for (int d = 0; d < NDT; ++d)
; #pragma unroll
;                     for (int s2 = 0; s2 < 2; ++s2) {
;                         const char* vp = sV + (sub * 32 + 16 * s2 + 4 * hh + q) * VS + (d * 32 + dblk * 16 + 4 * p) * 2;
;                         vf[d][s2] = cat8(tr_read(vp), tr_read(vp + 8 * VS));
;                     }
;                 if (NA && t < n0) {
;                     const float* brow = rpb + (kr - na.qr + 7) * 31 + 15 - qc;
; #pragma unroll
;                     for (int r = 0; r < 16; ++r) {
;                         const int kc = sub * 32 + (r & 3) + 8 * (r >> 2) + 4 * hh;
;                         const bool valid = (kc >= cs) && (kc < cs + 16);
;                         const int bi = valid ? kc : cs;
;                         const float bias = brow[bi];
;                         st[r] = valid ? st[r] + bias : -INFINITY;
;                     }
;                 }
;                 float mx = st[0];
; #pragma unroll
;                 for (int r = 1; r < 16; ++r) mx = fmaxf(mx, st[r]);
;                 mx = xor32_max(mx);
.LBB0_153:
	s_add_i32 s2, s0, 1
	s_and_b32 s2, s2, 1
	s_mul_i32 s2, s2, 0x8400
	v_add_u32_e32 v224, s2, v172
	v_add_u32_e32 v223, s2, v226
	v_add_u32_e32 v224, v224, v222
	v_add_u32_e32 v223, v223, v225
.Lmy_d2_top:
	s_add_i32 s0, s0, 1
	s_and_b32 s1, s0, 1
	ds_read_b128 v[140:143], v224
	ds_read_b128 v[144:147], v224 offset:32
	ds_read_b128 v[148:151], v224 offset:64
	ds_read_b128 v[152:155], v224 offset:96
	s_waitcnt lgkmcnt(3)
	v_mfma_f32_32x32x16_bf16 v[96:111], v[140:143], v[120:123], v[80:95]
	ds_read_b128 v[140:143], v224 offset:4608
	s_waitcnt lgkmcnt(3)
	v_mfma_f32_32x32x16_bf16 v[96:111], v[144:147], v[124:127], v[96:111]
	ds_read_b128 v[144:147], v224 offset:4640
	s_waitcnt lgkmcnt(3)
	v_mfma_f32_32x32x16_bf16 v[96:111], v[148:151], v[116:119], v[96:111]
	ds_read_b128 v[148:151], v224 offset:4672
	s_waitcnt lgkmcnt(3)
	v_mfma_f32_32x32x16_bf16 v[96:111], v[152:155], v[112:115], v[96:111]
	ds_read_b128 v[152:155], v224 offset:4704
	ds_read_b64_tr_b16 v[156:157], v223 offset:9216
	ds_read_b64_tr_b16 v[158:159], v223 offset:11776
	ds_read_b64_tr_b16 v[160:161], v223 offset:9280
	ds_read_b64_tr_b16 v[162:163], v223 offset:11840
	ds_read_b64_tr_b16 v[164:165], v223 offset:9344
	ds_read_b64_tr_b16 v[166:167], v223 offset:11904
	ds_read_b64_tr_b16 v[168:169], v223 offset:9408
	ds_read_b64_tr_b16 v[170:171], v223 offset:11968
	s_nop 2
	v_max3_f32 v239, v96, v97, v98
	v_max3_f32 v240, v104, v105, v106
	v_max3_f32 v239, v239, v99, v100
	v_max3_f32 v240, v240, v107, v108
	v_max3_f32 v239, v239, v101, v102
	v_max3_f32 v240, v240, v109, v110
	v_max3_f32 v239, v239, v103, v111
	v_max_f32_e32 v239, v239, v240
	v_cmp_lt_f32_e32 vcc, 0x41000000, v239
	s_cbranch_vccnz .Lmy_d2_rare0

; DI unsigned pk2(float a, float b) { f32x2 v = {a, b}; bfx2 r = __builtin_convertvector(v, bfx2); return __builtin_bit_cast(unsigned, r); }
; DI f32x16 mfma32(bf16x8 a, bf16x8 b, f32x16 c) { return __builtin_amdgcn_mfma_f32_32x32x16_bf16(a, b, c, 0, 0, 0); }
; template <int DQK, int DV, bool NA>
; DI void attend(const bf16_t* __restrict__ Q, int q0, const bf16_t* __restrict__ Kb, const bf16_t* __restrict__ Vb,
;                int s0, int n0, int s1, int n1, f32x16 (&o)[DV / 32], char* smem, NAInfo na) {
;     ...
; #pragma unroll
;                     for (int r = 0; r < 16; ++r) { st[r] = __builtin_amdgcn_exp2f(st[r]); rsum += st[r]; }
;                 }
;                 l += rsum;
;                 bf16x8 pf[2];
; #pragma unroll
;                 for (int s2 = 0; s2 < 2; ++s2) {
;                     u32x4 w;
;                     w.x = pk2(st[8 * s2], st[8 * s2 + 1]); w.y = pk2(st[8 * s2 + 2], st[8 * s2 + 3]);
;                     w.z = pk2(st[8 * s2 + 4], st[8 * s2 + 5]); w.w = pk2(st[8 * s2 + 6], st[8 * s2 + 7]);
;                     pf[s2] = __builtin_bit_cast(bf16x8, w);
;                 }
; #pragma unroll
;                 for (int d = 0; d < NDT; ++d)
; #pragma unroll
;                     for (int s2 = 0; s2 < 2; ++s2) o[d] = mfma32(vf[d][s2], pf[s2], o[d]);
;             }
;         }
;         if (t + 1 < nt) lwrite(smem + ((t & 1) ^ 1) * ATT_LDS);
;         if (t + 2 < nt) gload(t + 2);
;         __syncthreads();
;     }
.Lmy_d2_res1:
	v_exp_f32_e32 v64, v64
	v_exp_f32_e32 v65, v65
	v_exp_f32_e32 v66, v66
	v_exp_f32_e32 v67, v67
	v_exp_f32_e32 v68, v68
	v_exp_f32_e32 v69, v69
	v_exp_f32_e32 v70, v70
	v_exp_f32_e32 v71, v71
	v_add_f32_e32 v246, v64, v65
	v_add_f32_e32 v246, v246, v66
	v_add_f32_e32 v246, v246, v67
	v_add_f32_e32 v246, v246, v68
	v_add_f32_e32 v246, v246, v69
	v_add_f32_e32 v246, v246, v70
	v_add_f32_e32 v246, v246, v71
	v_cvt_pk_bf16_f32 v64, v64, v65
	v_cvt_pk_bf16_f32 v65, v66, v67
	v_cvt_pk_bf16_f32 v66, v68, v69
	v_cvt_pk_bf16_f32 v67, v70, v71
	v_exp_f32_e32 v72, v72
	v_exp_f32_e32 v73, v73
	s_waitcnt lgkmcnt(8)
	v_mfma_f32_32x32x16_bf16 v[48:63], v[156:159], v[64:67], v[48:63]
	v_exp_f32_e32 v74, v74
	v_exp_f32_e32 v75, v75
	v_exp_f32_e32 v76, v76
	v_exp_f32_e32 v77, v77
	v_exp_f32_e32 v78, v78
	v_mfma_f32_32x32x16_bf16 v[32:47], v[160:163], v[64:67], v[32:47]
	v_exp_f32_e32 v79, v79
	v_add_f32_e32 v247, v72, v73
	v_add_f32_e32 v247, v247, v74
	v_add_f32_e32 v247, v247, v75
	v_mfma_f32_32x32x16_bf16 v[16:31], v[164:167], v[64:67], v[16:31]
	v_add_f32_e32 v247, v247, v76
	v_add_f32_e32 v247, v247, v77
	v_add_f32_e32 v247, v247, v78
	v_add_f32_e32 v247, v247, v79
	v_mfma_f32_32x32x16_bf16 v[0:15], v[168:171], v[64:67], v[0:15]
	v_cvt_pk_bf16_f32 v72, v72, v73
	v_cvt_pk_bf16_f32 v73, v74, v75
	v_cvt_pk_bf16_f32 v74, v76, v77
	v_cvt_pk_bf16_f32 v75, v78, v79
	v_add_f32_e32 v244, v244, v245
	v_add_f32_e32 v246, v246, v247
	s_waitcnt lgkmcnt(0)
	v_mfma_f32_32x32x16_bf16 v[48:63], v[140:143], v[72:75], v[48:63]
	s_xor_b32 s1, s1, 1
	s_mul_i32 s1, s1, 0x8400
	v_add_f32_e32 v244, v244, v246
	v_add3_u32 v248, s1, v191, v192
	v_add3_u32 v249, s1, v193, v218
	v_add3_u32 v250, s1, v219, v221
	v_add_f32_e32 v188, v188, v244
	v_mfma_f32_32x32x16_bf16 v[32:47], v[144:147], v[72:75], v[32:47]
	v_add_u32_e32 v224, s1, v172
	v_add_u32_e32 v223, s1, v226
	v_add_u32_e32 v224, v224, v222
	v_add_u32_e32 v223, v223, v225
	s_waitcnt vmcnt(2)
	ds_write_b128 v248, v[128:131]
	v_mfma_f32_32x32x16_bf16 v[16:31], v[148:151], v[72:75], v[16:31]
	s_waitcnt vmcnt(1)
	ds_write_b128 v249, v[132:135] offset:9216
	s_waitcnt vmcnt(0)
	ds_write_b128 v250, v[136:139] offset:9216
	global_load_dwordx4 v[128:131], v[186:187], off
	global_load_dwordx4 v[132:135], v[184:185], off
	v_mfma_f32_32x32x16_bf16 v[0:15], v[152:155], v[72:75], v[0:15]
	global_load_dwordx4 v[136:139], v[180:181], off
	s_mov_b64 s[2:3], 0x4000
	v_lshl_add_u64 v[186:187], v[186:187], 0, s[82:83]
	v_lshl_add_u64 v[184:185], v[184:185], 0, s[2:3]
	v_lshl_add_u64 v[180:181], v[180:181], 0, s[2:3]
	v_cmp_eq_u32_e32 vcc, s0, v217
	v_mov_b32_e32 v96, s0
	s_or_b64 s[4:5], vcc, s[4:5]
	s_waitcnt lgkmcnt(0)
	s_barrier
	s_cbranch_vccz .Lmy_d2_top
	v_mov_b64_e32 v[64:65], v[80:81]
	v_mov_b64_e32 v[66:67], v[82:83]
	v_mov_b64_e32 v[68:69], v[84:85]
	v_mov_b64_e32 v[70:71], v[86:87]
	v_mov_b64_e32 v[72:73], v[88:89]
	v_mov_b64_e32 v[74:75], v[90:91]
	v_mov_b64_e32 v[76:77], v[92:93]
	v_mov_b64_e32 v[78:79], v[94:95]
	s_branch .LBB0_158
